# P5 vector segment: combined issue-slot trims (mask wait moved to matrix-segment tail, threshold test as one fmamk, alpha init in permlane slot)
# speedup vs baseline: 1.0084x; 1.0058x over previous
; __device__ __forceinline__ void sel_mask_tile(f32x16& p0, f32x16& p1, unsigned wlo, unsigned whi, int hi) {
;     const unsigned NEGB = 0xff800000u;
;     const unsigned lo = wlo >> (4 * hi), h2 = whi >> (4 * hi);
; #pragma unroll
;     for (int r = 0; r < 16; ++r) {
;         const int c = (r & 3) + 8 * (r >> 2);
;         const unsigned m0 = (unsigned)__builtin_amdgcn_sbfe((int)lo, c, 1), m1 = (unsigned)__builtin_amdgcn_sbfe((int)h2, c, 1);
;         p0[r] = __uint_as_float((__float_as_uint(p0[r]) & m0) | (NEGB & ~m0));
;         p1[r] = __uint_as_float((__float_as_uint(p1[r]) & m1) | (NEGB & ~m1));
;     }
; }
; __device__ __forceinline__ void partialSM(f32x16& p0, f32x16& p1, float& m_reg, float& mn, float& alpha) {
;     float pmax = p0[0];
; #pragma unroll
;     for (int r = 1; r < 16; ++r) pmax = fmaxf(pmax, p0[r]);
; #pragma unroll
;     for (int r = 0; r < 16; ++r) pmax = fmaxf(pmax, p1[r]);
;     { auto rr = __builtin_amdgcn_permlane32_swap(__float_as_uint(pmax), __float_as_uint(pmax), false, false);
;       pmax = fmaxf(__uint_as_float(rr[0]), __uint_as_float(rr[1])); }
;     constexpr float C2 = 1.4426950408889634f * SCALE;
;     if (__builtin_expect(__all((pmax - m_reg) * SCALE <= THR), 1)) { mn = m_reg; alpha = 1.f; }
;     else { mn = fmaxf(m_reg, pmax); alpha = __builtin_amdgcn_exp2f((m_reg - mn) * C2); m_reg = mn; }
.Lp5_k2_done:
	s_waitcnt lgkmcnt(0)
	s_barrier
	v_lshrrev_b32_e32 v160, v163, v146
	v_lshrrev_b32_e32 v161, v163, v147
	v_bfe_i32 v146, v160, 0, 1
	v_bfe_i32 v147, v161, 0, 1
	v_bitop3_b32 v146, v66, s74, v146 bitop3:0xe4
	v_bitop3_b32 v66, v82, s74, v147 bitop3:0xe4
	v_bfe_i32 v82, v160, 1, 1
	v_bfe_i32 v147, v161, 1, 1
	v_bitop3_b32 v82, v67, s74, v82 bitop3:0xe4
	v_bitop3_b32 v67, v83, s74, v147 bitop3:0xe4
	v_bfe_i32 v83, v160, 2, 1
	v_bfe_i32 v147, v161, 2, 1
	v_bitop3_b32 v83, v68, s74, v83 bitop3:0xe4
	v_bitop3_b32 v68, v84, s74, v147 bitop3:0xe4
	v_bfe_i32 v84, v160, 3, 1
	v_bfe_i32 v148, v161, 3, 1
	v_bitop3_b32 v147, v69, s74, v84 bitop3:0xe4
	v_bfe_i32 v84, v160, 8, 1
	v_bitop3_b32 v69, v85, s74, v148 bitop3:0xe4
	v_bfe_i32 v85, v161, 8, 1
	v_bitop3_b32 v148, v70, s74, v84 bitop3:0xe4
	v_bfe_i32 v84, v160, 9, 1
	v_bitop3_b32 v70, v86, s74, v85 bitop3:0xe4
	v_bfe_i32 v85, v161, 9, 1
	v_bitop3_b32 v149, v71, s74, v84 bitop3:0xe4
	v_bfe_i32 v84, v160, 10, 1
	v_bitop3_b32 v71, v87, s74, v85 bitop3:0xe4
	v_bfe_i32 v85, v161, 10, 1
	v_bitop3_b32 v87, v72, s74, v84 bitop3:0xe4
	v_bfe_i32 v84, v160, 11, 1
	v_bitop3_b32 v72, v88, s74, v85 bitop3:0xe4
	v_bfe_i32 v85, v161, 11, 1
	v_bitop3_b32 v88, v73, s74, v84 bitop3:0xe4
	v_bfe_i32 v73, v160, 16, 1
	v_bitop3_b32 v84, v89, s74, v85 bitop3:0xe4
	v_bfe_i32 v85, v161, 16, 1
	v_bitop3_b32 v89, v74, s74, v73 bitop3:0xe4
	v_bfe_i32 v73, v160, 17, 1
	v_bfe_i32 v74, v161, 17, 1
	v_bitop3_b32 v85, v90, s74, v85 bitop3:0xe4
	v_bitop3_b32 v90, v75, s74, v73 bitop3:0xe4
	v_bitop3_b32 v86, v91, s74, v74 bitop3:0xe4
	v_bfe_i32 v73, v160, 18, 1
	v_bfe_i32 v74, v161, 18, 1
	v_bitop3_b32 v91, v76, s74, v73 bitop3:0xe4
	v_bitop3_b32 v76, v92, s74, v74 bitop3:0xe4
	v_bfe_i32 v73, v160, 19, 1
	v_bfe_i32 v74, v161, 19, 1
	v_bitop3_b32 v92, v77, s74, v73 bitop3:0xe4
	v_bitop3_b32 v77, v93, s74, v74 bitop3:0xe4
	v_bfe_i32 v73, v160, 24, 1
	v_bfe_i32 v74, v161, 24, 1
	v_bitop3_b32 v93, v78, s74, v73 bitop3:0xe4
	v_bitop3_b32 v78, v94, s74, v74 bitop3:0xe4
	v_bfe_i32 v73, v160, 25, 1
	v_bfe_i32 v74, v161, 25, 1
	v_bitop3_b32 v79, v79, s74, v73 bitop3:0xe4
	v_bitop3_b32 v73, v95, s74, v74 bitop3:0xe4
	v_bfe_i32 v74, v160, 26, 1
	v_bfe_i32 v75, v161, 26, 1
	v_bitop3_b32 v80, v80, s74, v74 bitop3:0xe4
	v_bitop3_b32 v74, v96, s74, v75 bitop3:0xe4
	v_bfe_i32 v75, v160, 27, 1
	v_bfe_i32 v94, v161, 27, 1
	v_bitop3_b32 v81, v81, s74, v75 bitop3:0xe4
	v_bitop3_b32 v75, v97, s74, v94 bitop3:0xe4
	v_max_f32_e32 v94, v146, v82
	v_max3_f32 v94, v94, v83, v147
	v_max3_f32 v94, v94, v148, v149
	v_max3_f32 v94, v94, v87, v88
	v_max3_f32 v94, v94, v89, v90
	v_max3_f32 v94, v94, v91, v92
	v_max3_f32 v94, v94, v93, v79
	v_max3_f32 v94, v94, v80, v81
	v_max3_f32 v94, v94, v66, v67
	v_max3_f32 v94, v94, v68, v69
	v_max3_f32 v94, v94, v70, v71
	v_max3_f32 v94, v94, v72, v84
	v_max3_f32 v94, v94, v85, v86
	v_max3_f32 v94, v94, v76, v77
	v_max3_f32 v94, v94, v78, v73
	v_max3_f32 v94, v94, v74, v75
	v_mov_b32_e32 v95, v94
	v_mov_b32_e32 v208, 1.0
	s_nop 0
	v_permlane32_swap_b32_e32 v94, v95
	v_max_f32_e32 v94, v94, v95
	v_fmamk_f32 v95, v94, 0x3e0293ee, v190
	v_cmp_ge_f32_e32 vcc, 0x4138aa3b, v95
	s_cmp_eq_u64 vcc, exec
	s_cselect_b64 s[6:7], -1, 0
	s_cbranch_scc0 .Lp5_y1_slow

; __device__ __forceinline__ void sel_mask_tile(f32x16& p0, f32x16& p1, unsigned wlo, unsigned whi, int hi) {
;     const unsigned NEGB = 0xff800000u;
;     const unsigned lo = wlo >> (4 * hi), h2 = whi >> (4 * hi);
; #pragma unroll
;     for (int r = 0; r < 16; ++r) {
;         const int c = (r & 3) + 8 * (r >> 2);
;         const unsigned m0 = (unsigned)__builtin_amdgcn_sbfe((int)lo, c, 1), m1 = (unsigned)__builtin_amdgcn_sbfe((int)h2, c, 1);
;         p0[r] = __uint_as_float((__float_as_uint(p0[r]) & m0) | (NEGB & ~m0));
;         p1[r] = __uint_as_float((__float_as_uint(p1[r]) & m1) | (NEGB & ~m1));
;     }
; }
; __device__ __forceinline__ void partialSM(f32x16& p0, f32x16& p1, float& m_reg, float& mn, float& alpha) {
;     float pmax = p0[0];
; #pragma unroll
;     for (int r = 1; r < 16; ++r) pmax = fmaxf(pmax, p0[r]);
; #pragma unroll
;     for (int r = 0; r < 16; ++r) pmax = fmaxf(pmax, p1[r]);
;     { auto rr = __builtin_amdgcn_permlane32_swap(__float_as_uint(pmax), __float_as_uint(pmax), false, false);
;       pmax = fmaxf(__uint_as_float(rr[0]), __uint_as_float(rr[1])); }
;     constexpr float C2 = 1.4426950408889634f * SCALE;
;     if (__builtin_expect(__all((pmax - m_reg) * SCALE <= THR), 1)) { mn = m_reg; alpha = 1.f; }
;     else { mn = fmaxf(m_reg, pmax); alpha = __builtin_amdgcn_exp2f((m_reg - mn) * C2); m_reg = mn; }
.Lp5_k1_skip:
	s_waitcnt lgkmcnt(0)
	s_barrier
	v_lshrrev_b32_e32 v193, v163, v228
	v_bfe_i32 v192, v193, 0, 1
	v_bitop3_b32 v192, v82, s74, v192 bitop3:0xe4
	v_bfe_i32 v82, v193, 1, 1
	v_bitop3_b32 v146, v83, s74, v82 bitop3:0xe4
	v_bfe_i32 v82, v193, 2, 1
	v_bitop3_b32 v147, v84, s74, v82 bitop3:0xe4
	v_bfe_i32 v82, v193, 3, 1
	v_bitop3_b32 v148, v85, s74, v82 bitop3:0xe4
	v_bfe_i32 v82, v193, 8, 1
	v_bitop3_b32 v149, v86, s74, v82 bitop3:0xe4
	v_bfe_i32 v82, v193, 9, 1
	v_bitop3_b32 v150, v87, s74, v82 bitop3:0xe4
	v_bfe_i32 v82, v193, 10, 1
	v_bitop3_b32 v88, v88, s74, v82 bitop3:0xe4
	v_bfe_i32 v82, v193, 11, 1
	v_bitop3_b32 v89, v89, s74, v82 bitop3:0xe4
	v_bfe_i32 v82, v193, 16, 1
	v_bitop3_b32 v90, v90, s74, v82 bitop3:0xe4
	v_bfe_i32 v82, v193, 17, 1
	v_bitop3_b32 v91, v91, s74, v82 bitop3:0xe4
	v_bfe_i32 v82, v193, 18, 1
	v_bitop3_b32 v92, v92, s74, v82 bitop3:0xe4
	v_bfe_i32 v82, v193, 19, 1
	v_bitop3_b32 v93, v93, s74, v82 bitop3:0xe4
	v_bfe_i32 v82, v193, 24, 1
	v_bitop3_b32 v94, v94, s74, v82 bitop3:0xe4
	v_bfe_i32 v82, v193, 25, 1
	v_bitop3_b32 v95, v95, s74, v82 bitop3:0xe4
	v_bfe_i32 v82, v193, 26, 1
	v_bitop3_b32 v96, v96, s74, v82 bitop3:0xe4
	v_bfe_i32 v82, v193, 27, 1
	v_bitop3_b32 v97, v97, s74, v82 bitop3:0xe4
	v_max_f32_e32 v82, v192, v146
	v_max3_f32 v82, v82, v147, v148
	v_max3_f32 v82, v82, v149, v150
	v_max3_f32 v82, v82, v88, v89
	v_max3_f32 v82, v82, v90, v91
	v_lshrrev_b32_e32 v194, v163, v229
	v_max3_f32 v82, v82, v92, v93
	v_bfe_i32 v195, v194, 0, 1
	v_bfe_i32 v172, v194, 1, 1
	v_max3_f32 v82, v82, v94, v95
	v_bitop3_b32 v66, v66, s74, v195 bitop3:0xe4
	v_bfe_i32 v83, v194, 2, 1
	v_bfe_i32 v84, v194, 3, 1
	v_max3_f32 v230, v82, v96, v97
	v_bitop3_b32 v67, v67, s74, v172 bitop3:0xe4
	v_bfe_i32 v85, v194, 8, 1
	v_bfe_i32 v86, v194, 9, 1
	v_bitop3_b32 v82, v68, s74, v83 bitop3:0xe4
	v_max3_f32 v68, v230, v66, v67
	v_bitop3_b32 v83, v69, s74, v84 bitop3:0xe4
	v_bfe_i32 v87, v194, 10, 1
	v_bfe_i32 v151, v194, 11, 1
	v_bitop3_b32 v84, v70, s74, v85 bitop3:0xe4
	v_max3_f32 v68, v68, v82, v83
	v_bitop3_b32 v85, v71, s74, v86 bitop3:0xe4
	v_bfe_i32 v152, v194, 16, 1
	v_bfe_i32 v153, v194, 17, 1
	v_bitop3_b32 v86, v72, s74, v87 bitop3:0xe4
	v_max3_f32 v68, v68, v84, v85
	v_bitop3_b32 v87, v73, s74, v151 bitop3:0xe4
	v_bfe_i32 v154, v194, 18, 1
	v_bfe_i32 v155, v194, 19, 1
	v_bitop3_b32 v74, v74, s74, v152 bitop3:0xe4
	v_max3_f32 v69, v68, v86, v87
	v_bitop3_b32 v75, v75, s74, v153 bitop3:0xe4
	v_bfe_i32 v156, v194, 24, 1
	v_bfe_i32 v157, v194, 25, 1
	v_bitop3_b32 v68, v76, s74, v154 bitop3:0xe4
	v_max3_f32 v71, v69, v74, v75
	v_bitop3_b32 v69, v77, s74, v155 bitop3:0xe4
	v_bfe_i32 v230, v194, 26, 1
	v_bfe_i32 v231, v194, 27, 1
	v_bitop3_b32 v70, v78, s74, v156 bitop3:0xe4
	v_max3_f32 v73, v71, v68, v69
	v_bitop3_b32 v71, v79, s74, v157 bitop3:0xe4
	v_bitop3_b32 v72, v80, s74, v230 bitop3:0xe4
	v_max3_f32 v76, v73, v70, v71
	v_bitop3_b32 v73, v81, s74, v231 bitop3:0xe4
	v_max3_f32 v76, v76, v72, v73
	v_mov_b32_e32 v77, v76
	v_mov_b32_e32 v207, 1.0
	s_nop 0
	v_permlane32_swap_b32_e32 v76, v77
	v_max_f32_e32 v76, v76, v77
	v_fmamk_f32 v77, v76, 0x3e0293ee, v190
	v_cmp_ge_f32_e32 vcc, 0x4138aa3b, v77
	s_cmp_eq_u64 vcc, exec
	s_cselect_b64 s[6:7], -1, 0
